# GEMM K loop: stage DMAs issued earlier in the MFMA stream (behind MFMA 2,4,6,8,12,16 instead of 5,8,11,14,19,25)
# baseline (speedup 1.0000x reference)
.LBB0_246:
	s_add_i32 s10, s7, 0xffffa000
	s_cmp_lg_u32 s7, 0
	s_cselect_b32 s12, s10, 0xc000
	v_add_u32_e32 v131, s7, v150
	s_waitcnt vmcnt(6)
	s_barrier
	v_add_u32_e32 v133, s7, v149
	ds_read_b128 v[154:157], v131 offset:0
	ds_read_b128 v[158:161], v131 offset:0x400
	ds_read_b128 v[162:165], v131 offset:0x800
	ds_read_b128 v[166:169], v131 offset:0xc00
	v_add_u32_e32 v131, s12, v147
	ds_read_b128 v[170:173], v133 offset:0
	ds_read_b128 v[174:177], v133 offset:0x400
	ds_read_b128 v[178:181], v133 offset:0x800
	ds_read_b128 v[200:203], v133 offset:0xc00
	ds_read_b128 v[204:207], v133 offset:0x1000
	ds_read_b128 v[208:211], v133 offset:0x1400
	ds_read_b128 v[212:215], v133 offset:0x1800
	ds_read_b128 v[216:219], v133 offset:0x1c00
	s_add_u32 s10, s8, s50
	s_addc_u32 s11, s9, s51
	v_readfirstlane_b32 s13, v131
	s_add_u32 s64, s5, s100
	s_addc_u32 s65, s6, 0
	s_add_i32 s66, s7, 0x6000
	s_cmpk_lg_u32 s7, 0xc000
	s_cselect_b32 s7, s66, 0
	s_addk_i32 s100, 0x400
	s_add_u32 s50, s50, s60
	s_addc_u32 s51, s51, 0
	s_sub_i32 s68, s13, s12
	s_lshr_b32 s68, s68, 1
	s_add_i32 s68, s68, s12
	s_addk_i32 s68, 0x4000
	s_waitcnt lgkmcnt(4)
	v_mfma_f32_16x16x32_bf16 v[126:129], v[154:157], v[170:173], v[126:129]
	s_mov_b32 m0, s13
	v_mfma_f32_16x16x32_bf16 v[122:125], v[154:157], v[174:177], v[122:125]
	global_load_lds_dwordx4 v0, s[10:11]
	v_mfma_f32_16x16x32_bf16 v[118:121], v[154:157], v[178:181], v[118:121]
	s_add_u32 m0, s13, 0x400
	v_mfma_f32_16x16x32_bf16 v[114:117], v[154:157], v[200:203], v[114:117]
	global_load_lds_dwordx4 v130, s[10:11]
	v_mfma_f32_16x16x32_bf16 v[110:113], v[158:161], v[170:173], v[110:113]
	s_add_u32 m0, s13, 0x800
	v_mfma_f32_16x16x32_bf16 v[102:105], v[158:161], v[174:177], v[102:105]
	global_load_lds_dwordx4 v132, s[10:11]
	v_mfma_f32_16x16x32_bf16 v[94:97], v[158:161], v[178:181], v[94:97]
	s_add_u32 m0, s13, 0xc00
	v_mfma_f32_16x16x32_bf16 v[86:89], v[158:161], v[200:203], v[86:89]
	global_load_lds_dwordx4 v136, s[10:11]
	v_mfma_f32_16x16x32_bf16 v[78:81], v[162:165], v[170:173], v[78:81]
	v_mfma_f32_16x16x32_bf16 v[70:73], v[162:165], v[174:177], v[70:73]
	v_mfma_f32_16x16x32_bf16 v[62:65], v[162:165], v[178:181], v[62:65]
	s_mov_b32 m0, s68
	v_mfma_f32_16x16x32_bf16 v[54:57], v[162:165], v[200:203], v[54:57]
	global_load_lds_dwordx4 v138, s[64:65]
	v_mfma_f32_16x16x32_bf16 v[46:49], v[166:169], v[170:173], v[46:49]
	v_mfma_f32_16x16x32_bf16 v[38:41], v[166:169], v[174:177], v[38:41]
	v_mfma_f32_16x16x32_bf16 v[30:33], v[166:169], v[178:181], v[30:33]
	s_add_u32 m0, s68, 0x400
	v_mfma_f32_16x16x32_bf16 v[22:25], v[166:169], v[200:203], v[22:25]
	global_load_lds_dwordx4 v140, s[64:65]
	s_waitcnt lgkmcnt(0)
	v_mfma_f32_16x16x32_bf16 v[106:109], v[154:157], v[204:207], v[106:109]
	v_mfma_f32_16x16x32_bf16 v[98:101], v[154:157], v[208:211], v[98:101]
	v_mfma_f32_16x16x32_bf16 v[90:93], v[154:157], v[212:215], v[90:93]
	v_mfma_f32_16x16x32_bf16 v[82:85], v[154:157], v[216:219], v[82:85]
	v_mfma_f32_16x16x32_bf16 v[74:77], v[158:161], v[204:207], v[74:77]
	v_mfma_f32_16x16x32_bf16 v[66:69], v[158:161], v[208:211], v[66:69]
	v_mfma_f32_16x16x32_bf16 v[58:61], v[158:161], v[212:215], v[58:61]
	v_mfma_f32_16x16x32_bf16 v[50:53], v[158:161], v[216:219], v[50:53]
	v_mfma_f32_16x16x32_bf16 v[42:45], v[162:165], v[204:207], v[42:45]
	v_mfma_f32_16x16x32_bf16 v[34:37], v[162:165], v[208:211], v[34:37]
	v_mfma_f32_16x16x32_bf16 v[26:29], v[162:165], v[212:215], v[26:29]
	v_mfma_f32_16x16x32_bf16 v[18:21], v[162:165], v[216:219], v[18:21]
	v_mfma_f32_16x16x32_bf16 v[14:17], v[166:169], v[204:207], v[14:17]
	v_mfma_f32_16x16x32_bf16 v[10:13], v[166:169], v[208:211], v[10:13]
	v_mfma_f32_16x16x32_bf16 v[6:9], v[166:169], v[212:215], v[6:9]
	v_mfma_f32_16x16x32_bf16 v[2:5], v[166:169], v[216:219], v[2:5]
	s_cmpk_lg_i32 s100, 0x7800
	s_cbranch_scc1 .LBB0_246
	s_waitcnt vmcnt(6)
	s_barrier
	v_add_u32_e32 v0, s7, v150
	v_add_u32_e32 v140, s7, v149
	ds_read_b128 v[130:133], v0 offset:0
	ds_read_b128 v[136:139], v0 offset:0x400
	ds_read_b128 v[154:157], v0 offset:0x800
	ds_read_b128 v[158:161], v0 offset:0xc00
	ds_read_b128 v[162:165], v140 offset:0
	ds_read_b128 v[166:169], v140 offset:0x400
	ds_read_b128 v[170:173], v140 offset:0x800
	ds_read_b128 v[174:177], v140 offset:0xc00
	ds_read_b128 v[178:181], v140 offset:0x1000
	ds_read_b128 v[200:203], v140 offset:0x1400
	ds_read_b128 v[204:207], v140 offset:0x1800
	ds_read_b128 v[208:211], v140 offset:0x1c00
	s_lshl_b32 s49, s4, 8
	s_waitcnt lgkmcnt(4)
	s_nop 0
	v_mfma_f32_16x16x32_bf16 v[126:129], v[130:133], v[162:165], v[126:129]
	v_mfma_f32_16x16x32_bf16 v[118:121], v[130:133], v[170:173], v[118:121]
	v_mfma_f32_16x16x32_bf16 v[114:117], v[130:133], v[174:177], v[114:117]
	v_mfma_f32_16x16x32_bf16 v[110:113], v[136:139], v[162:165], v[110:113]
	v_mfma_f32_16x16x32_bf16 v[102:105], v[136:139], v[166:169], v[102:105]
	v_mfma_f32_16x16x32_bf16 v[94:97], v[136:139], v[170:173], v[94:97]
	v_mfma_f32_16x16x32_bf16 v[86:89], v[136:139], v[174:177], v[86:89]
	v_mfma_f32_16x16x32_bf16 v[70:73], v[154:157], v[166:169], v[70:73]
	v_mfma_f32_16x16x32_bf16 v[62:65], v[154:157], v[170:173], v[62:65]
	v_mfma_f32_16x16x32_bf16 v[54:57], v[154:157], v[174:177], v[54:57]
	v_mfma_f32_16x16x32_bf16 v[46:49], v[158:161], v[162:165], v[46:49]
	v_mfma_f32_16x16x32_bf16 v[38:41], v[158:161], v[166:169], v[38:41]
	v_mfma_f32_16x16x32_bf16 v[30:33], v[158:161], v[170:173], v[30:33]
	v_mfma_f32_16x16x32_bf16 v[22:25], v[158:161], v[174:177], v[22:25]
	v_mfma_f32_16x16x32_bf16 v[212:215], v[130:133], v[166:169], v[122:125]
	v_mfma_f32_16x16x32_bf16 v[216:219], v[154:157], v[162:165], v[78:81]
	s_waitcnt lgkmcnt(0)
	s_nop 0
	v_mfma_f32_16x16x32_bf16 v[174:177], v[136:139], v[178:181], v[74:77]
	v_mfma_f32_16x16x32_bf16 v[220:223], v[136:139], v[200:203], v[66:69]
	v_mfma_f32_16x16x32_bf16 v[224:227], v[136:139], v[204:207], v[58:61]
	v_mfma_f32_16x16x32_bf16 v[50:53], v[136:139], v[208:211], v[50:53]
	v_mfma_f32_16x16x32_bf16 v[136:139], v[154:157], v[178:181], v[42:45]
	v_mfma_f32_16x16x32_bf16 v[34:37], v[154:157], v[200:203], v[34:37]
	v_mfma_f32_16x16x32_bf16 v[6:9], v[158:161], v[204:207], v[6:9]
	v_mfma_f32_16x16x32_bf16 v[162:165], v[130:133], v[178:181], v[106:109]
	v_mfma_f32_16x16x32_bf16 v[166:169], v[130:133], v[200:203], v[98:101]
	v_mfma_f32_16x16x32_bf16 v[170:173], v[130:133], v[204:207], v[90:93]
	v_mfma_f32_16x16x32_bf16 v[130:133], v[130:133], v[208:211], v[82:85]
	v_mfma_f32_16x16x32_bf16 v[228:231], v[154:157], v[204:207], v[26:29]
	v_mfma_f32_16x16x32_bf16 v[154:157], v[154:157], v[208:211], v[18:21]
	v_mfma_f32_16x16x32_bf16 v[178:181], v[158:161], v[178:181], v[14:17]
	v_mfma_f32_16x16x32_bf16 v[200:203], v[158:161], v[200:203], v[10:13]
	v_mfma_f32_16x16x32_bf16 v[158:161], v[158:161], v[208:211], v[2:5]
	s_waitcnt vmcnt(0)
	s_barrier
	ds_read_b128 v[2:5], v151 offset:0
	ds_read_b128 v[14:17], v151 offset:0x400
	ds_read_b128 v[204:207], v151 offset:0x800
	ds_read_b128 v[208:211], v151 offset:0xc00
	ds_read_b128 v[10:13], v152 offset:0
	ds_read_b128 v[18:21], v152 offset:0x400
	ds_read_b128 v[26:29], v152 offset:0x800
	ds_read_b128 v[42:45], v152 offset:0xc00
	ds_read_b128 v[232:235], v152 offset:0x1000
	ds_read_b128 v[236:239], v152 offset:0x1400
	ds_read_b128 v[240:243], v152 offset:0x1800
	ds_read_b128 v[244:247], v152 offset:0x1c00
	s_nop 0
	s_waitcnt lgkmcnt(4)
	s_nop 0
	v_mfma_f32_16x16x32_bf16 v[122:125], v[2:5], v[10:13], v[126:129]
	v_mfma_f32_16x16x32_bf16 v[106:109], v[2:5], v[18:21], v[212:215]
	v_mfma_f32_16x16x32_bf16 v[90:93], v[2:5], v[26:29], v[118:121]
	v_mfma_f32_16x16x32_bf16 v[74:77], v[2:5], v[42:45], v[114:117]
	v_mfma_f32_16x16x32_bf16 v[126:129], v[14:17], v[10:13], v[110:113]
	v_mfma_f32_16x16x32_bf16 v[110:113], v[14:17], v[18:21], v[102:105]
	v_mfma_f32_16x16x32_bf16 v[94:97], v[14:17], v[26:29], v[94:97]
	v_mfma_f32_16x16x32_bf16 v[78:81], v[14:17], v[42:45], v[86:89]
	v_mfma_f32_16x16x32_bf16 v[114:117], v[204:207], v[10:13], v[216:219]
	v_mfma_f32_16x16x32_bf16 v[98:101], v[204:207], v[18:21], v[70:73]
	v_mfma_f32_16x16x32_bf16 v[82:85], v[204:207], v[26:29], v[62:65]
	v_mfma_f32_16x16x32_bf16 v[66:69], v[204:207], v[42:45], v[54:57]
	v_mfma_f32_16x16x32_bf16 v[118:121], v[208:211], v[10:13], v[46:49]
	v_mfma_f32_16x16x32_bf16 v[102:105], v[208:211], v[18:21], v[38:41]
	v_mfma_f32_16x16x32_bf16 v[86:89], v[208:211], v[26:29], v[30:33]
	v_mfma_f32_16x16x32_bf16 v[70:73], v[208:211], v[42:45], v[22:25]
	s_waitcnt lgkmcnt(0)
	s_nop 0
	v_mfma_f32_16x16x32_bf16 v[58:61], v[2:5], v[232:235], v[162:165]
	v_mfma_f32_16x16x32_bf16 v[42:45], v[2:5], v[236:239], v[166:169]
	v_mfma_f32_16x16x32_bf16 v[26:29], v[2:5], v[240:243], v[170:173]
	v_mfma_f32_16x16x32_bf16 v[10:13], v[2:5], v[244:247], v[130:133]
	v_mfma_f32_16x16x32_bf16 v[62:65], v[14:17], v[232:235], v[174:177]
	v_mfma_f32_16x16x32_bf16 v[46:49], v[14:17], v[236:239], v[220:223]
	v_mfma_f32_16x16x32_bf16 v[30:33], v[14:17], v[240:243], v[224:227]
	v_mfma_f32_16x16x32_bf16 v[14:17], v[14:17], v[244:247], v[50:53]
	v_mfma_f32_16x16x32_bf16 v[50:53], v[204:207], v[232:235], v[136:139]
	v_mfma_f32_16x16x32_bf16 v[34:37], v[204:207], v[236:239], v[34:37]
	v_mfma_f32_16x16x32_bf16 v[18:21], v[204:207], v[240:243], v[228:231]
	v_mfma_f32_16x16x32_bf16 v[2:5], v[204:207], v[244:247], v[154:157]
	v_mfma_f32_16x16x32_bf16 v[54:57], v[208:211], v[232:235], v[178:181]
	v_mfma_f32_16x16x32_bf16 v[38:41], v[208:211], v[236:239], v[200:203]
	v_mfma_f32_16x16x32_bf16 v[22:25], v[208:211], v[240:243], v[6:9]
	v_mfma_f32_16x16x32_bf16 v[6:9], v[208:211], v[244:247], v[158:161]
	v_mov_b32_e32 v136, v134
	s_mov_b64 s[50:51], -1
	s_and_b64 vcc, exec, s[22:23]
	s_barrier
	s_cbranch_vccz .LBB0_264
	s_and_b64 vcc, exec, s[0:1]
	s_cbranch_vccz .LBB0_250
	v_lshrrev_b32_e32 v0, 6, v136
	v_mul_lo_u32 v137, v0, s14
	v_and_b32_e32 v130, 15, v136
	v_and_or_b32 v0, v136, 48, v137
	s_movk_i32 s4, 0x90
	v_mad_u32_u24 v0, v130, s4, v0
	v_cvt_pk_bf16_f32 v130, v122, v123
	v_cvt_pk_bf16_f32 v131, v124, v125
	v_cvt_pk_bf16_f32 v132, v126, v127
	v_cvt_pk_bf16_f32 v133, v128, v129
	s_waitcnt vmcnt(0)
	ds_write_b128 v0, v[130:133]
	v_cvt_pk_bf16_f32 v130, v114, v115
	v_cvt_pk_bf16_f32 v131, v116, v117
	v_cvt_pk_bf16_f32 v132, v118, v119
	v_cvt_pk_bf16_f32 v133, v120, v121
	ds_write_b128 v0, v[130:133] offset:64
	v_cvt_pk_bf16_f32 v130, v106, v107
	v_cvt_pk_bf16_f32 v131, v108, v109
	v_cvt_pk_bf16_f32 v132, v110, v111
	v_cvt_pk_bf16_f32 v133, v112, v113
	ds_write_b128 v0, v[130:133] offset:2304
	v_cvt_pk_bf16_f32 v130, v98, v99
	v_cvt_pk_bf16_f32 v131, v100, v101
	v_cvt_pk_bf16_f32 v132, v102, v103
	v_cvt_pk_bf16_f32 v133, v104, v105
	ds_write_b128 v0, v[130:133] offset:2368
	v_cvt_pk_bf16_f32 v130, v90, v91
	v_cvt_pk_bf16_f32 v131, v92, v93
	v_cvt_pk_bf16_f32 v132, v94, v95
	v_cvt_pk_bf16_f32 v133, v96, v97
	ds_write_b128 v0, v[130:133] offset:4608
	v_cvt_pk_bf16_f32 v130, v82, v83
	v_cvt_pk_bf16_f32 v131, v84, v85
	v_cvt_pk_bf16_f32 v132, v86, v87
	v_cvt_pk_bf16_f32 v133, v88, v89
	ds_write_b128 v0, v[130:133] offset:4672
	v_cvt_pk_bf16_f32 v130, v74, v75
	v_cvt_pk_bf16_f32 v131, v76, v77
	v_cvt_pk_bf16_f32 v132, v78, v79
	v_cvt_pk_bf16_f32 v133, v80, v81
	ds_write_b128 v0, v[130:133] offset:6912
	v_cvt_pk_bf16_f32 v130, v66, v67
	v_cvt_pk_bf16_f32 v131, v68, v69
	v_cvt_pk_bf16_f32 v132, v70, v71
	v_cvt_pk_bf16_f32 v133, v72, v73
	ds_write_b128 v0, v[130:133] offset:6976
	v_cvt_pk_bf16_f32 v130, v58, v59
	v_cvt_pk_bf16_f32 v131, v60, v61
	v_cvt_pk_bf16_f32 v132, v62, v63
	v_cvt_pk_bf16_f32 v133, v64, v65
	ds_write_b128 v0, v[130:133] offset:9216
	v_cvt_pk_bf16_f32 v130, v50, v51
	v_cvt_pk_bf16_f32 v131, v52, v53
	v_cvt_pk_bf16_f32 v132, v54, v55
	v_cvt_pk_bf16_f32 v133, v56, v57
	ds_write_b128 v0, v[130:133] offset:9280
	v_cvt_pk_bf16_f32 v130, v42, v43
	v_cvt_pk_bf16_f32 v131, v44, v45
	v_cvt_pk_bf16_f32 v132, v46, v47
	v_cvt_pk_bf16_f32 v133, v48, v49
	ds_write_b128 v0, v[130:133] offset:11520
	v_cvt_pk_bf16_f32 v130, v34, v35
	v_cvt_pk_bf16_f32 v131, v36, v37
	v_cvt_pk_bf16_f32 v132, v38, v39
	v_cvt_pk_bf16_f32 v133, v40, v41
	ds_write_b128 v0, v[130:133] offset:11584
	v_cvt_pk_bf16_f32 v130, v26, v27
	v_cvt_pk_bf16_f32 v131, v28, v29
	v_cvt_pk_bf16_f32 v132, v30, v31
	v_cvt_pk_bf16_f32 v133, v32, v33
	ds_write_b128 v0, v[130:133] offset:13824
	v_cvt_pk_bf16_f32 v130, v18, v19
	v_cvt_pk_bf16_f32 v131, v20, v21
	v_cvt_pk_bf16_f32 v132, v22, v23
	v_cvt_pk_bf16_f32 v133, v24, v25
	ds_write_b128 v0, v[130:133] offset:13888
	v_cvt_pk_bf16_f32 v130, v10, v11
	v_cvt_pk_bf16_f32 v131, v12, v13
	v_cvt_pk_bf16_f32 v132, v14, v15
	v_cvt_pk_bf16_f32 v133, v16, v17
	ds_write_b128 v0, v[130:133] offset:16128
	v_cvt_pk_bf16_f32 v130, v2, v3
	v_cvt_pk_bf16_f32 v131, v4, v5
	v_cvt_pk_bf16_f32 v132, v6, v7
	v_cvt_pk_bf16_f32 v133, v8, v9
	ds_write_b128 v0, v[130:133] offset:16192
	v_and_b32_e32 v0, 0xffffff80, v136
	v_add_u32_e32 v130, s48, v0
	v_ashrrev_i32_e32 v131, 31, v130
	v_lshlrev_b64 v[130:131], 11, v[130:131]
	v_lshl_add_u64 v[130:131], s[38:39], 0, v[130:131]
	v_and_b32_e32 v0, 64, v136
	v_lshl_add_u64 v[130:131], s[46:47], 1, v[130:131]
	v_lshlrev_b32_e32 v0, 1, v0
	v_lshl_add_u64 v[138:139], v[130:131], 0, v[0:1]
	v_lshlrev_b32_e32 v0, 4, v136
	v_and_b32_e32 v0, 0x70, v0
	v_bfe_u32 v140, v136, 3, 3
	v_or_b32_e32 v130, v137, v0
	s_waitcnt lgkmcnt(0)
	v_mad_u32_u24 v137, v140, s4, v130
	ds_read_b128 v[66:69], v137
	ds_read_b128 v[70:73], v137 offset:1152
	ds_read_b128 v[74:77], v137 offset:2304
	ds_read_b128 v[78:81], v137 offset:3456
	ds_read_b128 v[82:85], v137 offset:4608
	ds_read_b128 v[86:89], v137 offset:5760
	ds_read_b128 v[90:93], v137 offset:6912
	ds_read_b128 v[94:97], v137 offset:8064
	ds_read_b128 v[98:101], v137 offset:9216
	ds_read_b128 v[102:105], v137 offset:10368
	ds_read_b128 v[106:109], v137 offset:11520
	ds_read_b128 v[110:113], v137 offset:12672
	ds_read_b128 v[114:117], v137 offset:13824
	ds_read_b128 v[118:121], v137 offset:14976
	ds_read_b128 v[122:125], v137 offset:16128
	ds_read_b128 v[126:129], v137 offset:17280
	v_lshl_add_u64 v[138:139], v[138:139], 0, v[0:1]
	v_lshlrev_b32_e32 v0, 11, v140
	v_lshl_add_u64 v[140:141], v[138:139], 0, v[0:1]
	s_mov_b64 s[50:51], 0
	s_waitcnt lgkmcnt(15)
	global_store_dwordx4 v[140:141], v[66:69], off
	v_or_b32_e32 v140, 0x4000, v0
	v_mov_b32_e32 v141, v1
	v_lshl_add_u64 v[140:141], v[138:139], 0, v[140:141]
	s_waitcnt lgkmcnt(14)
	global_store_dwordx4 v[140:141], v[70:73], off
	v_or_b32_e32 v140, 0x8000, v0
	v_mov_b32_e32 v141, v1
	v_lshl_add_u64 v[140:141], v[138:139], 0, v[140:141]
	s_waitcnt lgkmcnt(13)
	global_store_dwordx4 v[140:141], v[74:77], off
	v_or_b32_e32 v140, 0xc000, v0
	v_mov_b32_e32 v141, v1
	v_lshl_add_u64 v[140:141], v[138:139], 0, v[140:141]
	s_waitcnt lgkmcnt(12)
	global_store_dwordx4 v[140:141], v[78:81], off
	v_or_b32_e32 v140, 0x10000, v0
	v_mov_b32_e32 v141, v1
	v_lshl_add_u64 v[140:141], v[138:139], 0, v[140:141]
	s_waitcnt lgkmcnt(11)
	global_store_dwordx4 v[140:141], v[82:85], off
	v_or_b32_e32 v140, 0x14000, v0
	v_mov_b32_e32 v141, v1
	v_lshl_add_u64 v[140:141], v[138:139], 0, v[140:141]
	s_waitcnt lgkmcnt(10)
	global_store_dwordx4 v[140:141], v[86:89], off
	v_or_b32_e32 v140, 0x18000, v0
	v_mov_b32_e32 v141, v1
	v_lshl_add_u64 v[140:141], v[138:139], 0, v[140:141]
	s_waitcnt lgkmcnt(9)
	global_store_dwordx4 v[140:141], v[90:93], off
	v_or_b32_e32 v140, 0x1c000, v0
	v_mov_b32_e32 v141, v1
	v_lshl_add_u64 v[140:141], v[138:139], 0, v[140:141]
	s_waitcnt lgkmcnt(8)
	global_store_dwordx4 v[140:141], v[94:97], off
	v_or_b32_e32 v140, 0x20000, v0
	v_mov_b32_e32 v141, v1
	v_lshl_add_u64 v[140:141], v[138:139], 0, v[140:141]
	s_waitcnt lgkmcnt(7)
	global_store_dwordx4 v[140:141], v[98:101], off
	v_or_b32_e32 v140, 0x24000, v0
	v_mov_b32_e32 v141, v1
	v_lshl_add_u64 v[140:141], v[138:139], 0, v[140:141]
	s_waitcnt lgkmcnt(6)
	global_store_dwordx4 v[140:141], v[102:105], off
	v_or_b32_e32 v140, 0x28000, v0
	v_mov_b32_e32 v141, v1
	v_lshl_add_u64 v[140:141], v[138:139], 0, v[140:141]
	s_waitcnt lgkmcnt(5)
	global_store_dwordx4 v[140:141], v[106:109], off
	v_or_b32_e32 v140, 0x2c000, v0
	v_mov_b32_e32 v141, v1
	v_lshl_add_u64 v[140:141], v[138:139], 0, v[140:141]
	s_waitcnt lgkmcnt(4)
	global_store_dwordx4 v[140:141], v[110:113], off
	v_or_b32_e32 v140, 0x30000, v0
	v_mov_b32_e32 v141, v1
	v_lshl_add_u64 v[140:141], v[138:139], 0, v[140:141]
	s_waitcnt lgkmcnt(3)
	global_store_dwordx4 v[140:141], v[114:117], off
	v_or_b32_e32 v140, 0x34000, v0
	v_mov_b32_e32 v141, v1
	v_lshl_add_u64 v[140:141], v[138:139], 0, v[140:141]
	s_waitcnt lgkmcnt(2)
	global_store_dwordx4 v[140:141], v[118:121], off
	v_or_b32_e32 v140, 0x38000, v0
	v_mov_b32_e32 v141, v1
	v_lshl_add_u64 v[140:141], v[138:139], 0, v[140:141]
	v_or_b32_e32 v0, 0x3c000, v0
	s_waitcnt lgkmcnt(1)
	global_store_dwordx4 v[140:141], v[122:125], off
	v_lshl_add_u64 v[138:139], v[138:139], 0, v[0:1]
	s_waitcnt lgkmcnt(0)
	global_store_dwordx4 v[138:139], v[126:129], off
	s_waitcnt lgkmcnt(0)
	s_barrier
